# PEER unit loop: scalar-base row addressing, dot4 init without zeroing, hazard slots filled; v_cmp to v_cndmask wait-state fix in unit rotation
# baseline (speedup 1.0000x reference)
.Lxp_ukd:
	s_add_i32 s25, s25, 1
	s_cmp_lt_u32 s25, 4
	s_cbranch_scc1 .Lxp_tok
	s_waitcnt vmcnt(0)
	global_load_dword v70, v[246:247], off sc1
	s_nop 1
	v_mov_b32_dpp v64, v240 quad_perm:[1,0,3,2] row_mask:0xf bank_mask:0xf
	v_mov_b32_dpp v65, v241 quad_perm:[1,0,3,2] row_mask:0xf bank_mask:0xf
	s_mov_b32 vcc_lo, 0x99999999
	s_mov_b32 vcc_hi, 0x99999999
	v_min_u32_e32 v66, v240, v64
	v_max_u32_e32 v67, v240, v64
	v_min_u32_e32 v68, v241, v65
	v_max_u32_e32 v69, v241, v65
	v_cndmask_b32_e32 v240, v67, v66, vcc
	v_cndmask_b32_e32 v241, v69, v68, vcc
	s_nop 1
	v_mov_b32_dpp v64, v240 quad_perm:[2,3,0,1] row_mask:0xf bank_mask:0xf
	v_mov_b32_dpp v65, v241 quad_perm:[2,3,0,1] row_mask:0xf bank_mask:0xf
	s_mov_b32 vcc_lo, 0xc3c3c3c3
	s_mov_b32 vcc_hi, 0xc3c3c3c3
	v_min_u32_e32 v66, v240, v64
	v_max_u32_e32 v67, v240, v64
	v_min_u32_e32 v68, v241, v65
	v_max_u32_e32 v69, v241, v65
	v_cndmask_b32_e32 v240, v67, v66, vcc
	v_cndmask_b32_e32 v241, v69, v68, vcc
	s_nop 1
	v_mov_b32_dpp v64, v240 quad_perm:[1,0,3,2] row_mask:0xf bank_mask:0xf
	v_mov_b32_dpp v65, v241 quad_perm:[1,0,3,2] row_mask:0xf bank_mask:0xf
	s_mov_b32 vcc_lo, 0xa5a5a5a5
	s_mov_b32 vcc_hi, 0xa5a5a5a5
	v_min_u32_e32 v66, v240, v64
	v_max_u32_e32 v67, v240, v64
	v_min_u32_e32 v68, v241, v65
	v_max_u32_e32 v69, v241, v65
	v_cndmask_b32_e32 v240, v67, v66, vcc
	v_cndmask_b32_e32 v241, v69, v68, vcc
	ds_bpermute_b32 v64, v124, v240
	ds_bpermute_b32 v65, v124, v241
	s_mov_b32 vcc_lo, 0xf00ff00f
	s_mov_b32 vcc_hi, 0xf00ff00f
	s_waitcnt lgkmcnt(0)
	v_min_u32_e32 v66, v240, v64
	v_max_u32_e32 v67, v240, v64
	v_min_u32_e32 v68, v241, v65
	v_max_u32_e32 v69, v241, v65
	v_cndmask_b32_e32 v240, v67, v66, vcc
	v_cndmask_b32_e32 v241, v69, v68, vcc
	s_nop 1
	v_mov_b32_dpp v64, v240 quad_perm:[2,3,0,1] row_mask:0xf bank_mask:0xf
	v_mov_b32_dpp v65, v241 quad_perm:[2,3,0,1] row_mask:0xf bank_mask:0xf
	s_mov_b32 vcc_lo, 0xcc33cc33
	s_mov_b32 vcc_hi, 0xcc33cc33
	v_min_u32_e32 v66, v240, v64
	v_max_u32_e32 v67, v240, v64
	v_min_u32_e32 v68, v241, v65
	v_max_u32_e32 v69, v241, v65
	v_cndmask_b32_e32 v240, v67, v66, vcc
	v_cndmask_b32_e32 v241, v69, v68, vcc
	s_nop 1
	v_mov_b32_dpp v64, v240 quad_perm:[1,0,3,2] row_mask:0xf bank_mask:0xf
	v_mov_b32_dpp v65, v241 quad_perm:[1,0,3,2] row_mask:0xf bank_mask:0xf
	s_mov_b32 vcc_lo, 0xaa55aa55
	s_mov_b32 vcc_hi, 0xaa55aa55
	v_min_u32_e32 v66, v240, v64
	v_max_u32_e32 v67, v240, v64
	v_min_u32_e32 v68, v241, v65
	v_max_u32_e32 v69, v241, v65
	v_cndmask_b32_e32 v240, v67, v66, vcc
	v_cndmask_b32_e32 v241, v69, v68, vcc
	s_nop 1
	v_mov_b32_dpp v64, v240 row_ror:8 row_mask:0xf bank_mask:0xf
	v_mov_b32_dpp v65, v241 row_ror:8 row_mask:0xf bank_mask:0xf
	s_mov_b32 vcc_lo, 0xff0000ff
	s_mov_b32 vcc_hi, 0xff0000ff
	v_min_u32_e32 v66, v240, v64
	v_max_u32_e32 v67, v240, v64
	v_min_u32_e32 v68, v241, v65
	v_max_u32_e32 v69, v241, v65
	v_cndmask_b32_e32 v240, v67, v66, vcc
	v_cndmask_b32_e32 v241, v69, v68, vcc
	ds_bpermute_b32 v64, v124, v240
	ds_bpermute_b32 v65, v124, v241
	s_mov_b32 vcc_lo, 0xf0f00f0f
	s_mov_b32 vcc_hi, 0xf0f00f0f
	s_waitcnt lgkmcnt(0)
	v_min_u32_e32 v66, v240, v64
	v_max_u32_e32 v67, v240, v64
	v_min_u32_e32 v68, v241, v65
	v_max_u32_e32 v69, v241, v65
	v_cndmask_b32_e32 v240, v67, v66, vcc
	v_cndmask_b32_e32 v241, v69, v68, vcc
	s_nop 1
	v_mov_b32_dpp v64, v240 quad_perm:[2,3,0,1] row_mask:0xf bank_mask:0xf
	v_mov_b32_dpp v65, v241 quad_perm:[2,3,0,1] row_mask:0xf bank_mask:0xf
	s_mov_b32 vcc_lo, 0xcccc3333
	s_mov_b32 vcc_hi, 0xcccc3333
	v_min_u32_e32 v66, v240, v64
	v_max_u32_e32 v67, v240, v64
	v_min_u32_e32 v68, v241, v65
	v_max_u32_e32 v69, v241, v65
	v_cndmask_b32_e32 v240, v67, v66, vcc
	v_cndmask_b32_e32 v241, v69, v68, vcc
	s_nop 1
	v_mov_b32_dpp v64, v240 quad_perm:[1,0,3,2] row_mask:0xf bank_mask:0xf
	v_mov_b32_dpp v65, v241 quad_perm:[1,0,3,2] row_mask:0xf bank_mask:0xf
	s_mov_b32 vcc_lo, 0xaaaa5555
	s_mov_b32 vcc_hi, 0xaaaa5555
	v_min_u32_e32 v66, v240, v64
	v_max_u32_e32 v67, v240, v64
	v_min_u32_e32 v68, v241, v65
	v_max_u32_e32 v69, v241, v65
	v_cndmask_b32_e32 v240, v67, v66, vcc
	v_cndmask_b32_e32 v241, v69, v68, vcc
	ds_bpermute_b32 v64, v126, v240
	ds_bpermute_b32 v65, v126, v241
	s_mov_b32 vcc_lo, 0x0000ffff
	s_mov_b32 vcc_hi, 0xffff0000
	s_waitcnt lgkmcnt(0)
	v_min_u32_e32 v66, v240, v64
	v_max_u32_e32 v67, v240, v64
	v_min_u32_e32 v68, v241, v65
	v_max_u32_e32 v69, v241, v65
	v_cndmask_b32_e32 v240, v67, v66, vcc
	v_cndmask_b32_e32 v241, v69, v68, vcc
	s_nop 1
	v_mov_b32_dpp v64, v240 row_ror:8 row_mask:0xf bank_mask:0xf
	v_mov_b32_dpp v65, v241 row_ror:8 row_mask:0xf bank_mask:0xf
	s_mov_b32 vcc_lo, 0x00ff00ff
	s_mov_b32 vcc_hi, 0xff00ff00
	v_min_u32_e32 v66, v240, v64
	v_max_u32_e32 v67, v240, v64
	v_min_u32_e32 v68, v241, v65
	v_max_u32_e32 v69, v241, v65
	v_cndmask_b32_e32 v240, v67, v66, vcc
	v_cndmask_b32_e32 v241, v69, v68, vcc
	ds_bpermute_b32 v64, v124, v240
	ds_bpermute_b32 v65, v124, v241
	s_mov_b32 vcc_lo, 0x0f0f0f0f
	s_mov_b32 vcc_hi, 0xf0f0f0f0
	s_waitcnt lgkmcnt(0)
	v_min_u32_e32 v66, v240, v64
	v_max_u32_e32 v67, v240, v64
	v_min_u32_e32 v68, v241, v65
	v_max_u32_e32 v69, v241, v65
	v_cndmask_b32_e32 v240, v67, v66, vcc
	v_cndmask_b32_e32 v241, v69, v68, vcc
	s_nop 1
	v_mov_b32_dpp v64, v240 quad_perm:[2,3,0,1] row_mask:0xf bank_mask:0xf
	v_mov_b32_dpp v65, v241 quad_perm:[2,3,0,1] row_mask:0xf bank_mask:0xf
	s_mov_b32 vcc_lo, 0x33333333
	s_mov_b32 vcc_hi, 0xcccccccc
	v_min_u32_e32 v66, v240, v64
	v_max_u32_e32 v67, v240, v64
	v_min_u32_e32 v68, v241, v65
	v_max_u32_e32 v69, v241, v65
	v_cndmask_b32_e32 v240, v67, v66, vcc
	v_cndmask_b32_e32 v241, v69, v68, vcc
	s_nop 1
	v_mov_b32_dpp v64, v240 quad_perm:[1,0,3,2] row_mask:0xf bank_mask:0xf
	v_mov_b32_dpp v65, v241 quad_perm:[1,0,3,2] row_mask:0xf bank_mask:0xf
	s_mov_b32 vcc_lo, 0x55555555
	s_mov_b32 vcc_hi, 0xaaaaaaaa
	v_min_u32_e32 v66, v240, v64
	v_max_u32_e32 v67, v240, v64
	v_min_u32_e32 v68, v241, v65
	v_max_u32_e32 v69, v241, v65
	v_cndmask_b32_e32 v240, v67, v66, vcc
	v_cndmask_b32_e32 v241, v69, v68, vcc
	ds_bpermute_b32 v64, v127, v240
	ds_bpermute_b32 v65, v127, v241
	s_mov_b32 vcc_lo, 0xffffffff
	s_mov_b32 vcc_hi, 0x00000000
	s_waitcnt lgkmcnt(0)
	v_min_u32_e32 v66, v240, v64
	v_max_u32_e32 v67, v240, v64
	v_min_u32_e32 v68, v241, v65
	v_max_u32_e32 v69, v241, v65
	v_cndmask_b32_e32 v240, v67, v66, vcc
	v_cndmask_b32_e32 v241, v68, v69, vcc
	ds_bpermute_b32 v64, v126, v240
	ds_bpermute_b32 v65, v126, v241
	s_mov_b32 vcc_lo, 0x0000ffff
	s_mov_b32 vcc_hi, 0x0000ffff
	s_waitcnt lgkmcnt(0)
	v_min_u32_e32 v66, v240, v64
	v_max_u32_e32 v67, v240, v64
	v_min_u32_e32 v68, v241, v65
	v_max_u32_e32 v69, v241, v65
	v_cndmask_b32_e32 v240, v67, v66, vcc
	v_cndmask_b32_e32 v241, v68, v69, vcc
	s_nop 1
	v_mov_b32_dpp v64, v240 row_ror:8 row_mask:0xf bank_mask:0xf
	v_mov_b32_dpp v65, v241 row_ror:8 row_mask:0xf bank_mask:0xf
	s_mov_b32 vcc_lo, 0x00ff00ff
	s_mov_b32 vcc_hi, 0x00ff00ff
	v_min_u32_e32 v66, v240, v64
	v_max_u32_e32 v67, v240, v64
	v_min_u32_e32 v68, v241, v65
	v_max_u32_e32 v69, v241, v65
	v_cndmask_b32_e32 v240, v67, v66, vcc
	v_cndmask_b32_e32 v241, v68, v69, vcc
	ds_bpermute_b32 v64, v124, v240
	ds_bpermute_b32 v65, v124, v241
	s_mov_b32 vcc_lo, 0x0f0f0f0f
	s_mov_b32 vcc_hi, 0x0f0f0f0f
	s_waitcnt lgkmcnt(0)
	v_min_u32_e32 v66, v240, v64
	v_max_u32_e32 v67, v240, v64
	v_min_u32_e32 v68, v241, v65
	v_max_u32_e32 v69, v241, v65
	v_cndmask_b32_e32 v240, v67, v66, vcc
	v_cndmask_b32_e32 v241, v68, v69, vcc
	s_nop 1
	v_mov_b32_dpp v64, v240 quad_perm:[2,3,0,1] row_mask:0xf bank_mask:0xf
	v_mov_b32_dpp v65, v241 quad_perm:[2,3,0,1] row_mask:0xf bank_mask:0xf
	s_mov_b32 vcc_lo, 0x33333333
	s_mov_b32 vcc_hi, 0x33333333
	v_min_u32_e32 v66, v240, v64
	v_max_u32_e32 v67, v240, v64
	v_min_u32_e32 v68, v241, v65
	v_max_u32_e32 v69, v241, v65
	v_cndmask_b32_e32 v240, v67, v66, vcc
	v_cndmask_b32_e32 v241, v68, v69, vcc
	s_nop 1
	v_mov_b32_dpp v64, v240 quad_perm:[1,0,3,2] row_mask:0xf bank_mask:0xf
	v_mov_b32_dpp v65, v241 quad_perm:[1,0,3,2] row_mask:0xf bank_mask:0xf
	s_mov_b32 vcc_lo, 0x55555555
	s_mov_b32 vcc_hi, 0x55555555
	v_min_u32_e32 v66, v240, v64
	v_max_u32_e32 v67, v240, v64
	v_min_u32_e32 v68, v241, v65
	v_max_u32_e32 v69, v241, v65
	v_cndmask_b32_e32 v240, v67, v66, vcc
	v_cndmask_b32_e32 v241, v68, v69, vcc
	v_min_u32_e32 v66, v240, v241
	v_max_u32_e32 v241, v240, v241
	v_mov_b32_e32 v240, v66
	ds_bpermute_b32 v64, v127, v240
	ds_bpermute_b32 v65, v127, v241
	s_mov_b32 vcc_lo, 0xffffffff
	s_mov_b32 vcc_hi, 0x00000000
	s_waitcnt lgkmcnt(0)
	v_min_u32_e32 v66, v240, v64
	v_max_u32_e32 v67, v240, v64
	v_min_u32_e32 v68, v241, v65
	v_max_u32_e32 v69, v241, v65
	v_cndmask_b32_e32 v240, v67, v66, vcc
	v_cndmask_b32_e32 v241, v69, v68, vcc
	ds_bpermute_b32 v64, v126, v240
	ds_bpermute_b32 v65, v126, v241
	s_mov_b32 vcc_lo, 0x0000ffff
	s_mov_b32 vcc_hi, 0x0000ffff
	s_waitcnt lgkmcnt(0)
	v_min_u32_e32 v66, v240, v64
	v_max_u32_e32 v67, v240, v64
	v_min_u32_e32 v68, v241, v65
	v_max_u32_e32 v69, v241, v65
	v_cndmask_b32_e32 v240, v67, v66, vcc
	v_cndmask_b32_e32 v241, v69, v68, vcc
	s_nop 1
	v_mov_b32_dpp v64, v240 row_ror:8 row_mask:0xf bank_mask:0xf
	v_mov_b32_dpp v65, v241 row_ror:8 row_mask:0xf bank_mask:0xf
	s_mov_b32 vcc_lo, 0x00ff00ff
	s_mov_b32 vcc_hi, 0x00ff00ff
	v_min_u32_e32 v66, v240, v64
	v_max_u32_e32 v67, v240, v64
	v_min_u32_e32 v68, v241, v65
	v_max_u32_e32 v69, v241, v65
	v_cndmask_b32_e32 v240, v67, v66, vcc
	v_cndmask_b32_e32 v241, v69, v68, vcc
	ds_bpermute_b32 v64, v124, v240
	ds_bpermute_b32 v65, v124, v241
	s_mov_b32 vcc_lo, 0x0f0f0f0f
	s_mov_b32 vcc_hi, 0x0f0f0f0f
	s_waitcnt lgkmcnt(0)
	v_min_u32_e32 v66, v240, v64
	v_max_u32_e32 v67, v240, v64
	v_min_u32_e32 v68, v241, v65
	v_max_u32_e32 v69, v241, v65
	v_cndmask_b32_e32 v240, v67, v66, vcc
	v_cndmask_b32_e32 v241, v69, v68, vcc
	s_nop 1
	v_mov_b32_dpp v64, v240 quad_perm:[2,3,0,1] row_mask:0xf bank_mask:0xf
	v_mov_b32_dpp v65, v241 quad_perm:[2,3,0,1] row_mask:0xf bank_mask:0xf
	s_mov_b32 vcc_lo, 0x33333333
	s_mov_b32 vcc_hi, 0x33333333
	v_min_u32_e32 v66, v240, v64
	v_max_u32_e32 v67, v240, v64
	v_min_u32_e32 v68, v241, v65
	v_max_u32_e32 v69, v241, v65
	v_cndmask_b32_e32 v240, v67, v66, vcc
	v_cndmask_b32_e32 v241, v69, v68, vcc
	s_nop 1
	v_mov_b32_dpp v64, v240 quad_perm:[1,0,3,2] row_mask:0xf bank_mask:0xf
	v_mov_b32_dpp v65, v241 quad_perm:[1,0,3,2] row_mask:0xf bank_mask:0xf
	s_mov_b32 vcc_lo, 0x55555555
	s_mov_b32 vcc_hi, 0x55555555
	v_min_u32_e32 v66, v240, v64
	v_max_u32_e32 v67, v240, v64
	v_min_u32_e32 v68, v241, v65
	v_max_u32_e32 v69, v241, v65
	v_cndmask_b32_e32 v240, v67, v66, vcc
	v_cndmask_b32_e32 v241, v69, v68, vcc
	s_waitcnt vmcnt(0)
	v_readfirstlane_b32 s2, v70
	s_and_b32 s2, s2, 0x3fff
	s_mov_b32 s97, s2
	s_lshl_b32 s3, s2, 7
	v_cmp_gt_u32_e32 vcc, s3, v240
	s_nop 1
	s_bcnt1_i32_b64 s2, vcc
	v_cmp_gt_u32_e32 vcc, s3, v241
	s_nop 1
	s_bcnt1_i32_b64 s3, vcc
	s_add_i32 s2, s2, s3
	v_add_u32_e32 v64, s2, v60
	v_and_b32_e32 v64, 0x7f, v64
	v_and_b32_e32 v65, 63, v64
	v_lshlrev_b32_e32 v65, 2, v65
	ds_bpermute_b32 v66, v65, v240
	ds_bpermute_b32 v67, v65, v241
	v_cmp_gt_u32_e32 vcc, 64, v64
	s_waitcnt lgkmcnt(0)
	s_nop 1
	v_cndmask_b32_e32 v240, v67, v66, vcc
	v_cndmask_b32_e32 v241, v66, v67, vcc
	v_mov_b32_e32 v132, v70
	v_lshlrev_b32_e32 v252, 4, v60
	s_nop 1
	v_readlane_b32 s2, v240, 0
	s_and_b32 s3, s2, 31
	s_lshl_b32 s3, s3, 5
	s_bfe_u32 s94, s2, 0x20005
	s_lshl_b32 s2, s94, 11
	s_add_i32 s3, s3, s2
	s_load_dwordx8 s[84:91], s[36:37], s3
	s_waitcnt lgkmcnt(0)
	s_and_b32 s84, s84, 0x3fff
	s_lshl_b32 s2, s84, 11
	s_add_u32 s2, s18, s2
	s_addc_u32 s3, s19, 0
	global_load_dwordx4 v[8:11], v252, s[2:3]
	global_load_dwordx4 v[40:43], v252, s[2:3] offset:1024
	s_lshl_b32 s2, s84, 2
	v_writelane_b32 v147, s2, 0
	v_writelane_b32 v0, s85, 0
	s_and_b32 s86, s86, 0x3fff
	s_lshl_b32 s2, s86, 11
	s_add_u32 s2, s18, s2
	s_addc_u32 s3, s19, 0
	global_load_dwordx4 v[16:19], v252, s[2:3]
	global_load_dwordx4 v[44:47], v252, s[2:3] offset:1024
	s_lshl_b32 s2, s86, 2
	v_writelane_b32 v147, s2, 1
	v_writelane_b32 v0, s87, 1
	s_and_b32 s88, s88, 0x3fff
	s_lshl_b32 s2, s88, 11
	s_add_u32 s2, s18, s2
	s_addc_u32 s3, s19, 0
	global_load_dwordx4 v[32:35], v252, s[2:3]
	global_load_dwordx4 v[48:51], v252, s[2:3] offset:1024
	s_lshl_b32 s2, s88, 2
	v_writelane_b32 v147, s2, 2
	v_writelane_b32 v0, s89, 2
	s_and_b32 s90, s90, 0x3fff
	s_lshl_b32 s2, s90, 11
	s_add_u32 s2, s18, s2
	s_addc_u32 s3, s19, 0
	global_load_dwordx4 v[36:39], v252, s[2:3]
	global_load_dwordx4 v[52:55], v252, s[2:3] offset:1024
	s_lshl_b32 s2, s90, 2
	v_writelane_b32 v147, s2, 3
	v_writelane_b32 v0, s91, 3
	global_load_dword v138, v147, s[44:45]
	global_load_dword v139, v147, s[46:47]
	s_mov_b32 s33, s94
	v_readlane_b32 s2, v240, 1
	s_and_b32 s3, s2, 31
	s_lshl_b32 s3, s3, 5
	s_bfe_u32 s94, s2, 0x20005
	s_lshl_b32 s2, s94, 11
	s_add_i32 s3, s3, s2
	s_load_dwordx8 s[84:91], s[36:37], s3
	s_waitcnt lgkmcnt(0)
	s_and_b32 s84, s84, 0x3fff
	s_lshl_b32 s2, s84, 11
	s_add_u32 s2, s18, s2
	s_addc_u32 s3, s19, 0
	global_load_dwordx4 v[152:155], v252, s[2:3]
	global_load_dwordx4 v[12:15], v252, s[2:3] offset:1024
	s_lshl_b32 s2, s84, 2
	v_writelane_b32 v147, s2, 0
	v_writelane_b32 v1, s85, 0
	s_and_b32 s86, s86, 0x3fff
	s_lshl_b32 s2, s86, 11
	s_add_u32 s2, s18, s2
	s_addc_u32 s3, s19, 0
	global_load_dwordx4 v[156:159], v252, s[2:3]
	global_load_dwordx4 v[20:23], v252, s[2:3] offset:1024
	s_lshl_b32 s2, s86, 2
	v_writelane_b32 v147, s2, 1
	v_writelane_b32 v1, s87, 1
	s_and_b32 s88, s88, 0x3fff
	s_lshl_b32 s2, s88, 11
	s_add_u32 s2, s18, s2
	s_addc_u32 s3, s19, 0
	global_load_dwordx4 v[160:163], v252, s[2:3]
	global_load_dwordx4 v[24:27], v252, s[2:3] offset:1024
	s_lshl_b32 s2, s88, 2
	v_writelane_b32 v147, s2, 2
	v_writelane_b32 v1, s89, 2
	s_and_b32 s90, s90, 0x3fff
	s_lshl_b32 s2, s90, 11
	s_add_u32 s2, s18, s2
	s_addc_u32 s3, s19, 0
	global_load_dwordx4 v[164:167], v252, s[2:3]
	global_load_dwordx4 v[28:31], v252, s[2:3] offset:1024
	s_lshl_b32 s2, s90, 2
	v_writelane_b32 v147, s2, 3
	v_writelane_b32 v1, s91, 3
	global_load_dword v140, v147, s[44:45]
	global_load_dword v141, v147, s[46:47]
	s_mov_b32 s80, s94
	v_readlane_b32 s2, v240, 2
	s_and_b32 s3, s2, 31
	s_lshl_b32 s3, s3, 5
	s_bfe_u32 s94, s2, 0x20005
	s_lshl_b32 s2, s94, 11
	s_add_i32 s3, s3, s2
	s_load_dwordx8 s[84:91], s[36:37], s3
	s_mov_b32 s81, s94
	v_mov_b32_e32 v90, 0
	v_mov_b32_e32 v91, 0
	v_mov_b32_e32 v92, 0
	v_mov_b32_e32 v93, 0
	v_mov_b32_e32 v94, 0
	v_mov_b32_e32 v95, 0
	v_mov_b32_e32 v96, 0
	v_mov_b32_e32 v97, 0
	v_mov_b32_e32 v98, 0
	v_mov_b32_e32 v99, 0
	v_mov_b32_e32 v100, 0
	v_mov_b32_e32 v101, 0
	v_mov_b32_e32 v102, 0
	v_mov_b32_e32 v103, 0
	v_mov_b32_e32 v104, 0
	v_mov_b32_e32 v105, 0
	v_mov_b32_e32 v142, 0
	v_readlane_b32 s3, v244, s33
	s_nop 1
	v_mov_b32_e32 v137, s3
	s_cmp_eq_u32 s33, 0
	s_cbranch_scc1 .Lxp_ixq0
	s_cmp_eq_u32 s33, 1
	s_cbranch_scc1 .Lxp_ixq1
	s_cmp_eq_u32 s33, 2
	s_cbranch_scc1 .Lxp_ixq2
	v_mov_b32_e32 v133, v236
	v_mov_b32_e32 v134, v237
	v_mov_b32_e32 v135, v238
	v_mov_b32_e32 v136, v239
	s_branch .Lxp_ixqd

.Lxp_syncda:
	s_and_b32 s84, s84, 0x3fff
	s_lshl_b32 s2, s84, 11
	s_add_u32 s2, s18, s2
	s_addc_u32 s3, s19, 0
	global_load_dwordx4 v[72:75], v252, s[2:3]
	global_load_dwordx4 v[64:67], v252, s[2:3] offset:1024
	s_lshl_b32 s2, s84, 2
	v_writelane_b32 v147, s2, 0
	v_writelane_b32 v2, s85, 0
	s_and_b32 s86, s86, 0x3fff
	s_lshl_b32 s2, s86, 11
	s_add_u32 s2, s18, s2
	s_addc_u32 s3, s19, 0
	global_load_dwordx4 v[76:79], v252, s[2:3]
	global_load_dwordx4 v[68:71], v252, s[2:3] offset:1024
	s_lshl_b32 s2, s86, 2
	v_writelane_b32 v147, s2, 1
	v_writelane_b32 v2, s87, 1
	s_and_b32 s88, s88, 0x3fff
	s_lshl_b32 s2, s88, 11
	s_add_u32 s2, s18, s2
	s_addc_u32 s3, s19, 0
	global_load_dwordx4 v[80:83], v252, s[2:3]
	global_load_dwordx4 v[4:7], v252, s[2:3] offset:1024
	s_lshl_b32 s2, s88, 2
	v_writelane_b32 v147, s2, 2
	v_writelane_b32 v2, s89, 2
	s_and_b32 s90, s90, 0x3fff
	s_lshl_b32 s2, s90, 11
	s_add_u32 s2, s18, s2
	s_addc_u32 s3, s19, 0
	global_load_dwordx4 v[84:87], v252, s[2:3]
	global_load_dwordx4 v[128:131], v252, s[2:3] offset:1024
	s_lshl_b32 s2, s90, 2
	v_writelane_b32 v147, s2, 3
	v_writelane_b32 v2, s91, 3
	global_load_dword v88, v147, s[44:45]
	global_load_dword v89, v147, s[46:47]
	v_dot4_i32_i8 v149, v8, v133, 0
	v_dot4_i32_i8 v150, v16, v133, 0
	v_dot4_i32_i8 v151, v32, v133, 0
	v_dot4_i32_i8 v148, v36, v133, 0
	v_dot4c_i32_i8_e32 v149, v9, v134
	v_dot4c_i32_i8_e32 v150, v17, v134
	v_dot4c_i32_i8_e32 v151, v33, v134
	v_dot4c_i32_i8_e32 v148, v37, v134
	v_dot4c_i32_i8_e32 v149, v10, v135
	v_dot4c_i32_i8_e32 v150, v18, v135
	v_dot4c_i32_i8_e32 v151, v34, v135
	v_dot4c_i32_i8_e32 v148, v38, v135
	v_dot4c_i32_i8_e32 v149, v11, v136
	v_dot4c_i32_i8_e32 v150, v19, v136
	v_dot4c_i32_i8_e32 v151, v35, v136
	v_dot4c_i32_i8_e32 v148, v39, v136
	s_add_i32 s3, s25, 3
	s_min_u32 s3, s3, 0x7f
	s_cmp_lt_u32 s3, 64
	s_cselect_b64 vcc, -1, 0
	s_nop 0
	v_cndmask_b32_e32 v249, v241, v240, vcc
	s_nop 1
	v_readlane_b32 s2, v249, s3
	s_and_b32 s3, s2, 31
	s_lshl_b32 s3, s3, 5
	s_bfe_u32 s94, s2, 0x20005
	s_lshl_b32 s2, s94, 11
	s_add_i32 s3, s3, s2
	s_load_dwordx8 s[84:91], s[36:37], s3
	v_cndmask_b32_e64 v143, v149, v150, s[0:1]
	v_cndmask_b32_e64 v144, v150, v149, s[0:1]
	v_cndmask_b32_e64 v145, v151, v148, s[0:1]
	v_cndmask_b32_e64 v146, v148, v151, s[0:1]
	s_nop 1
	v_add_u32_dpp v144, v143, v144 quad_perm:[1,0,3,2] row_mask:0xf bank_mask:0xf
	v_add_u32_dpp v146, v145, v146 quad_perm:[1,0,3,2] row_mask:0xf bank_mask:0xf
	s_nop 1
	v_cndmask_b32_e64 v143, v144, v146, s[6:7]
	v_cndmask_b32_e64 v145, v146, v144, s[6:7]
	s_nop 1
	v_add_u32_dpp v145, v143, v145 quad_perm:[2,3,0,1] row_mask:0xf bank_mask:0xf
	s_nop 1
	v_add_u32_dpp v145, v145, v145 row_ror:4 row_mask:0xf bank_mask:0xf
	s_nop 1
	v_add_u32_dpp v145, v145, v145 row_ror:8 row_mask:0xf bank_mask:0xf
	s_nop 1
	ds_bpermute_b32 v143, v126, v145
	s_waitcnt lgkmcnt(0)
	v_add_u32_e32 v145, v145, v143
	ds_bpermute_b32 v143, v127, v145
	s_waitcnt lgkmcnt(0)
	v_add_u32_e32 v145, v145, v143
	v_cvt_f32_i32_e32 v56, v145
	v_mul_f32_e32 v59, v138, v56
	v_mul_f32_e32 v59, v137, v59
	v_mul_f32_e32 v56, 0x3f3504f3, v59
	v_fma_f32 v143, |v56|, s66, v120
	v_fma_f32 v143, |v56|, v143, s67
	v_fma_f32 v143, |v56|, v143, s68
	v_fma_f32 v143, |v56|, v143, s69
	v_fma_f32 v143, |v56|, v143, s70
	v_fma_f32 v143, |v56|, v143, s71
	v_fma_f32 v143, |v56|, v143, |v56|
	v_mul_f32_e32 v144, 0xbfb8aa3b, v143
	v_fma_f32 v146, v143, s72, -v144
	v_rndne_f32_e32 v3, v144
	v_fmac_f32_e32 v146, 0xb2a5705f, v143
	v_sub_f32_e32 v144, v144, v3
	v_add_f32_e32 v144, v144, v146
	v_cvt_i32_f32_e32 v146, v3
	v_exp_f32_e32 v144, v144
	v_cmp_nlt_f32_e32 vcc, s73, v143
	v_ldexp_f32 v144, v144, v146
	s_nop 0
	v_cndmask_b32_e32 v144, 0, v144, vcc
	v_cmp_ngt_f32_e32 vcc, s74, v143
	s_nop 1
	v_cndmask_b32_e32 v143, v121, v144, vcc
	v_sub_f32_e32 v143, 1.0, v143
	v_mul_f32_e32 v168, v56, v56
	v_fmamk_f32 v169, v168, 0xba1345e1, v117
	v_fmaak_f32 v169, v168, v169, 0xbcdac9b8
	v_fmaak_f32 v169, v168, v169, 0x3de703be
	v_fmaak_f32 v169, v168, v169, 0xbec09330
	v_fmaak_f32 v168, v168, v169, 0x3e0375d0
	v_fma_f32 v168, |v56|, v168, |v56|
	v_cmp_nlt_f32_e64 vcc, |v56|, 1.0
	s_nop 1
	v_cndmask_b32_e32 v143, v168, v143, vcc
	v_bfi_b32 v146, s75, v143, v56
	v_mul_f32_e32 v145, 0.5, v59
	v_add_f32_e32 v146, 1.0, v146
	v_mul_f32_e32 v145, v145, v146
	v_mul_f32_e32 v144, v0, v145
	v_mul_f32_e32 v143, v139, v144
	s_nop 1
	v_readlane_b32 s40, v143, 0
	v_readlane_b32 s38, v143, 1
	v_readlane_b32 s42, v143, 2
	v_readlane_b32 s2, v143, 3
	s_nop 1
	v_add_f32_e32 v142, s40, v142
	v_add_f32_e32 v142, s38, v142
	v_add_f32_e32 v142, s42, v142
	v_add_f32_e32 v142, s2, v142
	v_cvt_f32_ubyte1_e32 v169, v40
	v_cvt_f32_ubyte0_e32 v168, v40
	v_pk_fma_f32 v[104:105], s[40:41], v[168:169], v[104:105] op_sel_hi:[0,1,1]
	v_cvt_f32_ubyte1_e32 v171, v44
	v_cvt_f32_ubyte0_e32 v170, v44
	v_pk_fma_f32 v[104:105], s[38:39], v[170:171], v[104:105] op_sel_hi:[0,1,1]
	v_cvt_f32_ubyte1_e32 v169, v48
	v_cvt_f32_ubyte0_e32 v168, v48
	v_pk_fma_f32 v[104:105], s[42:43], v[168:169], v[104:105] op_sel_hi:[0,1,1]
	v_cvt_f32_ubyte1_e32 v171, v52
	v_cvt_f32_ubyte0_e32 v170, v52
	v_pk_fma_f32 v[104:105], s[2:3], v[170:171], v[104:105] op_sel_hi:[0,1,1]
	v_cvt_f32_ubyte3_e32 v169, v40
	v_cvt_f32_ubyte2_e32 v168, v40
	v_pk_fma_f32 v[102:103], s[40:41], v[168:169], v[102:103] op_sel_hi:[0,1,1]
	v_cvt_f32_ubyte3_e32 v171, v44
	v_cvt_f32_ubyte2_e32 v170, v44
	v_pk_fma_f32 v[102:103], s[38:39], v[170:171], v[102:103] op_sel_hi:[0,1,1]
	v_cvt_f32_ubyte3_e32 v169, v48
	v_cvt_f32_ubyte2_e32 v168, v48
	v_pk_fma_f32 v[102:103], s[42:43], v[168:169], v[102:103] op_sel_hi:[0,1,1]
	v_cvt_f32_ubyte3_e32 v171, v52
	v_cvt_f32_ubyte2_e32 v170, v52
	v_pk_fma_f32 v[102:103], s[2:3], v[170:171], v[102:103] op_sel_hi:[0,1,1]
	v_cvt_f32_ubyte1_e32 v169, v41
	v_cvt_f32_ubyte0_e32 v168, v41
	v_pk_fma_f32 v[98:99], s[40:41], v[168:169], v[98:99] op_sel_hi:[0,1,1]
	v_cvt_f32_ubyte1_e32 v171, v45
	v_cvt_f32_ubyte0_e32 v170, v45
	v_pk_fma_f32 v[98:99], s[38:39], v[170:171], v[98:99] op_sel_hi:[0,1,1]
	v_cvt_f32_ubyte1_e32 v169, v49
	v_cvt_f32_ubyte0_e32 v168, v49
	v_pk_fma_f32 v[98:99], s[42:43], v[168:169], v[98:99] op_sel_hi:[0,1,1]
	v_cvt_f32_ubyte1_e32 v171, v53
	v_cvt_f32_ubyte0_e32 v170, v53
	v_pk_fma_f32 v[98:99], s[2:3], v[170:171], v[98:99] op_sel_hi:[0,1,1]
	v_cvt_f32_ubyte3_e32 v169, v41
	v_cvt_f32_ubyte2_e32 v168, v41
	v_pk_fma_f32 v[100:101], s[40:41], v[168:169], v[100:101] op_sel_hi:[0,1,1]
	v_cvt_f32_ubyte3_e32 v171, v45
	v_cvt_f32_ubyte2_e32 v170, v45
	v_pk_fma_f32 v[100:101], s[38:39], v[170:171], v[100:101] op_sel_hi:[0,1,1]
	v_cvt_f32_ubyte3_e32 v169, v49
	v_cvt_f32_ubyte2_e32 v168, v49
	v_pk_fma_f32 v[100:101], s[42:43], v[168:169], v[100:101] op_sel_hi:[0,1,1]
	v_cvt_f32_ubyte3_e32 v171, v53
	v_cvt_f32_ubyte2_e32 v170, v53
	v_pk_fma_f32 v[100:101], s[2:3], v[170:171], v[100:101] op_sel_hi:[0,1,1]
	v_cvt_f32_ubyte1_e32 v169, v42
	v_cvt_f32_ubyte0_e32 v168, v42
	v_pk_fma_f32 v[94:95], s[40:41], v[168:169], v[94:95] op_sel_hi:[0,1,1]
	v_cvt_f32_ubyte1_e32 v171, v46
	v_cvt_f32_ubyte0_e32 v170, v46
	v_pk_fma_f32 v[94:95], s[38:39], v[170:171], v[94:95] op_sel_hi:[0,1,1]
	v_cvt_f32_ubyte1_e32 v169, v50
	v_cvt_f32_ubyte0_e32 v168, v50
	v_pk_fma_f32 v[94:95], s[42:43], v[168:169], v[94:95] op_sel_hi:[0,1,1]
	v_cvt_f32_ubyte1_e32 v171, v54
	v_cvt_f32_ubyte0_e32 v170, v54
	v_pk_fma_f32 v[94:95], s[2:3], v[170:171], v[94:95] op_sel_hi:[0,1,1]
	v_cvt_f32_ubyte3_e32 v169, v42
	v_cvt_f32_ubyte2_e32 v168, v42
	v_pk_fma_f32 v[96:97], s[40:41], v[168:169], v[96:97] op_sel_hi:[0,1,1]
	v_cvt_f32_ubyte3_e32 v171, v46
	v_cvt_f32_ubyte2_e32 v170, v46
	v_pk_fma_f32 v[96:97], s[38:39], v[170:171], v[96:97] op_sel_hi:[0,1,1]
	v_cvt_f32_ubyte3_e32 v169, v50
	v_cvt_f32_ubyte2_e32 v168, v50
	v_pk_fma_f32 v[96:97], s[42:43], v[168:169], v[96:97] op_sel_hi:[0,1,1]
	v_cvt_f32_ubyte3_e32 v171, v54
	v_cvt_f32_ubyte2_e32 v170, v54
	v_pk_fma_f32 v[96:97], s[2:3], v[170:171], v[96:97] op_sel_hi:[0,1,1]
	v_cvt_f32_ubyte1_e32 v169, v43
	v_cvt_f32_ubyte0_e32 v168, v43
	v_pk_fma_f32 v[90:91], s[40:41], v[168:169], v[90:91] op_sel_hi:[0,1,1]
	v_cvt_f32_ubyte1_e32 v171, v47
	v_cvt_f32_ubyte0_e32 v170, v47
	v_pk_fma_f32 v[90:91], s[38:39], v[170:171], v[90:91] op_sel_hi:[0,1,1]
	v_cvt_f32_ubyte1_e32 v169, v51
	v_cvt_f32_ubyte0_e32 v168, v51
	v_pk_fma_f32 v[90:91], s[42:43], v[168:169], v[90:91] op_sel_hi:[0,1,1]
	v_cvt_f32_ubyte1_e32 v171, v55
	v_cvt_f32_ubyte0_e32 v170, v55
	v_pk_fma_f32 v[90:91], s[2:3], v[170:171], v[90:91] op_sel_hi:[0,1,1]
	v_cvt_f32_ubyte3_e32 v169, v43
	v_cvt_f32_ubyte2_e32 v168, v43
	v_pk_fma_f32 v[92:93], s[40:41], v[168:169], v[92:93] op_sel_hi:[0,1,1]
	v_cvt_f32_ubyte3_e32 v171, v47
	v_cvt_f32_ubyte2_e32 v170, v47
	v_pk_fma_f32 v[92:93], s[38:39], v[170:171], v[92:93] op_sel_hi:[0,1,1]
	v_cvt_f32_ubyte3_e32 v169, v51
	v_cvt_f32_ubyte2_e32 v168, v51
	v_pk_fma_f32 v[92:93], s[42:43], v[168:169], v[92:93] op_sel_hi:[0,1,1]
	v_cvt_f32_ubyte3_e32 v171, v55
	v_cvt_f32_ubyte2_e32 v170, v55
	v_pk_fma_f32 v[92:93], s[2:3], v[170:171], v[92:93] op_sel_hi:[0,1,1]
	s_waitcnt vmcnt(10) lgkmcnt(0)
	s_cmp_eq_u32 s80, s33
	s_cbranch_scc1 .Lxp_noswa
	s_lshl_b32 s2, s33, 12
	v_add_u32_e32 v249, s2, v248
	ds_write_b128 v249, v[90:93]
	ds_write_b128 v249, v[94:97] offset:1024
	ds_write_b128 v249, v[98:101] offset:2048
	ds_write_b128 v249, v[102:105] offset:3072
	v_cmp_eq_u32_e32 vcc, s33, v60
	s_nop 1
	v_cndmask_b32_e32 v243, v243, v142, vcc
	s_lshl_b32 s2, s80, 12
	v_add_u32_e32 v249, s2, v248
	ds_read_b128 v[90:93], v249
	ds_read_b128 v[94:97], v249 offset:1024
	ds_read_b128 v[98:101], v249 offset:2048
	ds_read_b128 v[102:105], v249 offset:3072
	s_nop 0
	v_readlane_b32 s2, v243, s80
	v_readlane_b32 s3, v244, s80
	s_nop 1
	v_mov_b32_e32 v142, s2
	v_mov_b32_e32 v137, s3
	s_cmp_eq_u32 s80, 0
	s_cbranch_scc1 .Lxp_lxqa0
	s_cmp_eq_u32 s80, 1
	s_cbranch_scc1 .Lxp_lxqa1
	s_cmp_eq_u32 s80, 2
	s_cbranch_scc1 .Lxp_lxqa2
	v_mov_b32_e32 v133, v236
	v_mov_b32_e32 v134, v237
	v_mov_b32_e32 v135, v238
	v_mov_b32_e32 v136, v239
	s_branch .Lxp_lxqad

.Lxp_syncdb:
	s_and_b32 s84, s84, 0x3fff
	s_lshl_b32 s2, s84, 11
	s_add_u32 s2, s18, s2
	s_addc_u32 s3, s19, 0
	global_load_dwordx4 v[8:11], v252, s[2:3]
	global_load_dwordx4 v[40:43], v252, s[2:3] offset:1024
	s_lshl_b32 s2, s84, 2
	v_writelane_b32 v147, s2, 0
	v_writelane_b32 v0, s85, 0
	s_and_b32 s86, s86, 0x3fff
	s_lshl_b32 s2, s86, 11
	s_add_u32 s2, s18, s2
	s_addc_u32 s3, s19, 0
	global_load_dwordx4 v[16:19], v252, s[2:3]
	global_load_dwordx4 v[44:47], v252, s[2:3] offset:1024
	s_lshl_b32 s2, s86, 2
	v_writelane_b32 v147, s2, 1
	v_writelane_b32 v0, s87, 1
	s_and_b32 s88, s88, 0x3fff
	s_lshl_b32 s2, s88, 11
	s_add_u32 s2, s18, s2
	s_addc_u32 s3, s19, 0
	global_load_dwordx4 v[32:35], v252, s[2:3]
	global_load_dwordx4 v[48:51], v252, s[2:3] offset:1024
	s_lshl_b32 s2, s88, 2
	v_writelane_b32 v147, s2, 2
	v_writelane_b32 v0, s89, 2
	s_and_b32 s90, s90, 0x3fff
	s_lshl_b32 s2, s90, 11
	s_add_u32 s2, s18, s2
	s_addc_u32 s3, s19, 0
	global_load_dwordx4 v[36:39], v252, s[2:3]
	global_load_dwordx4 v[52:55], v252, s[2:3] offset:1024
	s_lshl_b32 s2, s90, 2
	v_writelane_b32 v147, s2, 3
	v_writelane_b32 v0, s91, 3
	global_load_dword v138, v147, s[44:45]
	global_load_dword v139, v147, s[46:47]
	v_dot4_i32_i8 v149, v152, v133, 0
	v_dot4_i32_i8 v150, v156, v133, 0
	v_dot4_i32_i8 v151, v160, v133, 0
	v_dot4_i32_i8 v148, v164, v133, 0
	v_dot4c_i32_i8_e32 v149, v153, v134
	v_dot4c_i32_i8_e32 v150, v157, v134
	v_dot4c_i32_i8_e32 v151, v161, v134
	v_dot4c_i32_i8_e32 v148, v165, v134
	v_dot4c_i32_i8_e32 v149, v154, v135
	v_dot4c_i32_i8_e32 v150, v158, v135
	v_dot4c_i32_i8_e32 v151, v162, v135
	v_dot4c_i32_i8_e32 v148, v166, v135
	v_dot4c_i32_i8_e32 v149, v155, v136
	v_dot4c_i32_i8_e32 v150, v159, v136
	v_dot4c_i32_i8_e32 v151, v163, v136
	v_dot4c_i32_i8_e32 v148, v167, v136
	s_add_i32 s3, s25, 3
	s_min_u32 s3, s3, 0x7f
	s_cmp_lt_u32 s3, 64
	s_cselect_b64 vcc, -1, 0
	s_nop 0
	v_cndmask_b32_e32 v249, v241, v240, vcc
	s_nop 1
	v_readlane_b32 s2, v249, s3
	s_and_b32 s3, s2, 31
	s_lshl_b32 s3, s3, 5
	s_bfe_u32 s94, s2, 0x20005
	s_lshl_b32 s2, s94, 11
	s_add_i32 s3, s3, s2
	s_load_dwordx8 s[84:91], s[36:37], s3
	v_cndmask_b32_e64 v143, v149, v150, s[0:1]
	v_cndmask_b32_e64 v144, v150, v149, s[0:1]
	v_cndmask_b32_e64 v145, v151, v148, s[0:1]
	v_cndmask_b32_e64 v146, v148, v151, s[0:1]
	s_nop 1
	v_add_u32_dpp v144, v143, v144 quad_perm:[1,0,3,2] row_mask:0xf bank_mask:0xf
	v_add_u32_dpp v146, v145, v146 quad_perm:[1,0,3,2] row_mask:0xf bank_mask:0xf
	s_nop 1
	v_cndmask_b32_e64 v143, v144, v146, s[6:7]
	v_cndmask_b32_e64 v145, v146, v144, s[6:7]
	s_nop 1
	v_add_u32_dpp v145, v143, v145 quad_perm:[2,3,0,1] row_mask:0xf bank_mask:0xf
	s_nop 1
	v_add_u32_dpp v145, v145, v145 row_ror:4 row_mask:0xf bank_mask:0xf
	s_nop 1
	v_add_u32_dpp v145, v145, v145 row_ror:8 row_mask:0xf bank_mask:0xf
	s_nop 1
	ds_bpermute_b32 v143, v126, v145
	s_waitcnt lgkmcnt(0)
	v_add_u32_e32 v145, v145, v143
	ds_bpermute_b32 v143, v127, v145
	s_waitcnt lgkmcnt(0)
	v_add_u32_e32 v145, v145, v143
	v_cvt_f32_i32_e32 v56, v145
	v_mul_f32_e32 v59, v140, v56
	v_mul_f32_e32 v59, v137, v59
	v_mul_f32_e32 v56, 0x3f3504f3, v59
	v_fma_f32 v143, |v56|, s66, v120
	v_fma_f32 v143, |v56|, v143, s67
	v_fma_f32 v143, |v56|, v143, s68
	v_fma_f32 v143, |v56|, v143, s69
	v_fma_f32 v143, |v56|, v143, s70
	v_fma_f32 v143, |v56|, v143, s71
	v_fma_f32 v143, |v56|, v143, |v56|
	v_mul_f32_e32 v144, 0xbfb8aa3b, v143
	v_fma_f32 v146, v143, s72, -v144
	v_rndne_f32_e32 v3, v144
	v_fmac_f32_e32 v146, 0xb2a5705f, v143
	v_sub_f32_e32 v144, v144, v3
	v_add_f32_e32 v144, v144, v146
	v_cvt_i32_f32_e32 v146, v3
	v_exp_f32_e32 v144, v144
	v_cmp_nlt_f32_e32 vcc, s73, v143
	v_ldexp_f32 v144, v144, v146
	s_nop 0
	v_cndmask_b32_e32 v144, 0, v144, vcc
	v_cmp_ngt_f32_e32 vcc, s74, v143
	s_nop 1
	v_cndmask_b32_e32 v143, v121, v144, vcc
	v_sub_f32_e32 v143, 1.0, v143
	v_mul_f32_e32 v168, v56, v56
	v_fmamk_f32 v169, v168, 0xba1345e1, v117
	v_fmaak_f32 v169, v168, v169, 0xbcdac9b8
	v_fmaak_f32 v169, v168, v169, 0x3de703be
	v_fmaak_f32 v169, v168, v169, 0xbec09330
	v_fmaak_f32 v168, v168, v169, 0x3e0375d0
	v_fma_f32 v168, |v56|, v168, |v56|
	v_cmp_nlt_f32_e64 vcc, |v56|, 1.0
	s_nop 1
	v_cndmask_b32_e32 v143, v168, v143, vcc
	v_bfi_b32 v146, s75, v143, v56
	v_mul_f32_e32 v145, 0.5, v59
	v_add_f32_e32 v146, 1.0, v146
	v_mul_f32_e32 v145, v145, v146
	v_mul_f32_e32 v144, v1, v145
	v_mul_f32_e32 v143, v141, v144
	s_nop 1
	v_readlane_b32 s40, v143, 0
	v_readlane_b32 s38, v143, 1
	v_readlane_b32 s42, v143, 2
	v_readlane_b32 s2, v143, 3
	s_nop 1
	v_add_f32_e32 v142, s40, v142
	v_add_f32_e32 v142, s38, v142
	v_add_f32_e32 v142, s42, v142
	v_add_f32_e32 v142, s2, v142
	v_cvt_f32_ubyte1_e32 v169, v12
	v_cvt_f32_ubyte0_e32 v168, v12
	v_pk_fma_f32 v[104:105], s[40:41], v[168:169], v[104:105] op_sel_hi:[0,1,1]
	v_cvt_f32_ubyte1_e32 v171, v20
	v_cvt_f32_ubyte0_e32 v170, v20
	v_pk_fma_f32 v[104:105], s[38:39], v[170:171], v[104:105] op_sel_hi:[0,1,1]
	v_cvt_f32_ubyte1_e32 v169, v24
	v_cvt_f32_ubyte0_e32 v168, v24
	v_pk_fma_f32 v[104:105], s[42:43], v[168:169], v[104:105] op_sel_hi:[0,1,1]
	v_cvt_f32_ubyte1_e32 v171, v28
	v_cvt_f32_ubyte0_e32 v170, v28
	v_pk_fma_f32 v[104:105], s[2:3], v[170:171], v[104:105] op_sel_hi:[0,1,1]
	v_cvt_f32_ubyte3_e32 v169, v12
	v_cvt_f32_ubyte2_e32 v168, v12
	v_pk_fma_f32 v[102:103], s[40:41], v[168:169], v[102:103] op_sel_hi:[0,1,1]
	v_cvt_f32_ubyte3_e32 v171, v20
	v_cvt_f32_ubyte2_e32 v170, v20
	v_pk_fma_f32 v[102:103], s[38:39], v[170:171], v[102:103] op_sel_hi:[0,1,1]
	v_cvt_f32_ubyte3_e32 v169, v24
	v_cvt_f32_ubyte2_e32 v168, v24
	v_pk_fma_f32 v[102:103], s[42:43], v[168:169], v[102:103] op_sel_hi:[0,1,1]
	v_cvt_f32_ubyte3_e32 v171, v28
	v_cvt_f32_ubyte2_e32 v170, v28
	v_pk_fma_f32 v[102:103], s[2:3], v[170:171], v[102:103] op_sel_hi:[0,1,1]
	v_cvt_f32_ubyte1_e32 v169, v13
	v_cvt_f32_ubyte0_e32 v168, v13
	v_pk_fma_f32 v[98:99], s[40:41], v[168:169], v[98:99] op_sel_hi:[0,1,1]
	v_cvt_f32_ubyte1_e32 v171, v21
	v_cvt_f32_ubyte0_e32 v170, v21
	v_pk_fma_f32 v[98:99], s[38:39], v[170:171], v[98:99] op_sel_hi:[0,1,1]
	v_cvt_f32_ubyte1_e32 v169, v25
	v_cvt_f32_ubyte0_e32 v168, v25
	v_pk_fma_f32 v[98:99], s[42:43], v[168:169], v[98:99] op_sel_hi:[0,1,1]
	v_cvt_f32_ubyte1_e32 v171, v29
	v_cvt_f32_ubyte0_e32 v170, v29
	v_pk_fma_f32 v[98:99], s[2:3], v[170:171], v[98:99] op_sel_hi:[0,1,1]
	v_cvt_f32_ubyte3_e32 v169, v13
	v_cvt_f32_ubyte2_e32 v168, v13
	v_pk_fma_f32 v[100:101], s[40:41], v[168:169], v[100:101] op_sel_hi:[0,1,1]
	v_cvt_f32_ubyte3_e32 v171, v21
	v_cvt_f32_ubyte2_e32 v170, v21
	v_pk_fma_f32 v[100:101], s[38:39], v[170:171], v[100:101] op_sel_hi:[0,1,1]
	v_cvt_f32_ubyte3_e32 v169, v25
	v_cvt_f32_ubyte2_e32 v168, v25
	v_pk_fma_f32 v[100:101], s[42:43], v[168:169], v[100:101] op_sel_hi:[0,1,1]
	v_cvt_f32_ubyte3_e32 v171, v29
	v_cvt_f32_ubyte2_e32 v170, v29
	v_pk_fma_f32 v[100:101], s[2:3], v[170:171], v[100:101] op_sel_hi:[0,1,1]
	v_cvt_f32_ubyte1_e32 v169, v14
	v_cvt_f32_ubyte0_e32 v168, v14
	v_pk_fma_f32 v[94:95], s[40:41], v[168:169], v[94:95] op_sel_hi:[0,1,1]
	v_cvt_f32_ubyte1_e32 v171, v22
	v_cvt_f32_ubyte0_e32 v170, v22
	v_pk_fma_f32 v[94:95], s[38:39], v[170:171], v[94:95] op_sel_hi:[0,1,1]
	v_cvt_f32_ubyte1_e32 v169, v26
	v_cvt_f32_ubyte0_e32 v168, v26
	v_pk_fma_f32 v[94:95], s[42:43], v[168:169], v[94:95] op_sel_hi:[0,1,1]
	v_cvt_f32_ubyte1_e32 v171, v30
	v_cvt_f32_ubyte0_e32 v170, v30
	v_pk_fma_f32 v[94:95], s[2:3], v[170:171], v[94:95] op_sel_hi:[0,1,1]
	v_cvt_f32_ubyte3_e32 v169, v14
	v_cvt_f32_ubyte2_e32 v168, v14
	v_pk_fma_f32 v[96:97], s[40:41], v[168:169], v[96:97] op_sel_hi:[0,1,1]
	v_cvt_f32_ubyte3_e32 v171, v22
	v_cvt_f32_ubyte2_e32 v170, v22
	v_pk_fma_f32 v[96:97], s[38:39], v[170:171], v[96:97] op_sel_hi:[0,1,1]
	v_cvt_f32_ubyte3_e32 v169, v26
	v_cvt_f32_ubyte2_e32 v168, v26
	v_pk_fma_f32 v[96:97], s[42:43], v[168:169], v[96:97] op_sel_hi:[0,1,1]
	v_cvt_f32_ubyte3_e32 v171, v30
	v_cvt_f32_ubyte2_e32 v170, v30
	v_pk_fma_f32 v[96:97], s[2:3], v[170:171], v[96:97] op_sel_hi:[0,1,1]
	v_cvt_f32_ubyte1_e32 v169, v15
	v_cvt_f32_ubyte0_e32 v168, v15
	v_pk_fma_f32 v[90:91], s[40:41], v[168:169], v[90:91] op_sel_hi:[0,1,1]
	v_cvt_f32_ubyte1_e32 v171, v23
	v_cvt_f32_ubyte0_e32 v170, v23
	v_pk_fma_f32 v[90:91], s[38:39], v[170:171], v[90:91] op_sel_hi:[0,1,1]
	v_cvt_f32_ubyte1_e32 v169, v27
	v_cvt_f32_ubyte0_e32 v168, v27
	v_pk_fma_f32 v[90:91], s[42:43], v[168:169], v[90:91] op_sel_hi:[0,1,1]
	v_cvt_f32_ubyte1_e32 v171, v31
	v_cvt_f32_ubyte0_e32 v170, v31
	v_pk_fma_f32 v[90:91], s[2:3], v[170:171], v[90:91] op_sel_hi:[0,1,1]
	v_cvt_f32_ubyte3_e32 v169, v15
	v_cvt_f32_ubyte2_e32 v168, v15
	v_pk_fma_f32 v[92:93], s[40:41], v[168:169], v[92:93] op_sel_hi:[0,1,1]
	v_cvt_f32_ubyte3_e32 v171, v23
	v_cvt_f32_ubyte2_e32 v170, v23
	v_pk_fma_f32 v[92:93], s[38:39], v[170:171], v[92:93] op_sel_hi:[0,1,1]
	v_cvt_f32_ubyte3_e32 v169, v27
	v_cvt_f32_ubyte2_e32 v168, v27
	v_pk_fma_f32 v[92:93], s[42:43], v[168:169], v[92:93] op_sel_hi:[0,1,1]
	v_cvt_f32_ubyte3_e32 v171, v31
	v_cvt_f32_ubyte2_e32 v170, v31
	v_pk_fma_f32 v[92:93], s[2:3], v[170:171], v[92:93] op_sel_hi:[0,1,1]
	s_waitcnt vmcnt(10) lgkmcnt(0)
	s_cmp_eq_u32 s80, s33
	s_cbranch_scc1 .Lxp_noswb
	s_lshl_b32 s2, s33, 12
	v_add_u32_e32 v249, s2, v248
	ds_write_b128 v249, v[90:93]
	ds_write_b128 v249, v[94:97] offset:1024
	ds_write_b128 v249, v[98:101] offset:2048
	ds_write_b128 v249, v[102:105] offset:3072
	v_cmp_eq_u32_e32 vcc, s33, v60
	s_nop 1
	v_cndmask_b32_e32 v243, v243, v142, vcc
	s_lshl_b32 s2, s80, 12
	v_add_u32_e32 v249, s2, v248
	ds_read_b128 v[90:93], v249
	ds_read_b128 v[94:97], v249 offset:1024
	ds_read_b128 v[98:101], v249 offset:2048
	ds_read_b128 v[102:105], v249 offset:3072
	s_nop 0
	v_readlane_b32 s2, v243, s80
	v_readlane_b32 s3, v244, s80
	s_nop 1
	v_mov_b32_e32 v142, s2
	v_mov_b32_e32 v137, s3
	s_cmp_eq_u32 s80, 0
	s_cbranch_scc1 .Lxp_lxqb0
	s_cmp_eq_u32 s80, 1
	s_cbranch_scc1 .Lxp_lxqb1
	s_cmp_eq_u32 s80, 2
	s_cbranch_scc1 .Lxp_lxqb2
	v_mov_b32_e32 v133, v236
	v_mov_b32_e32 v134, v237
	v_mov_b32_e32 v135, v238
	v_mov_b32_e32 v136, v239
	s_branch .Lxp_lxqbd

.Lxp_syncdc:
	s_and_b32 s84, s84, 0x3fff
	s_lshl_b32 s2, s84, 11
	s_add_u32 s2, s18, s2
	s_addc_u32 s3, s19, 0
	global_load_dwordx4 v[152:155], v252, s[2:3]
	global_load_dwordx4 v[12:15], v252, s[2:3] offset:1024
	s_lshl_b32 s2, s84, 2
	v_writelane_b32 v147, s2, 0
	v_writelane_b32 v1, s85, 0
	s_and_b32 s86, s86, 0x3fff
	s_lshl_b32 s2, s86, 11
	s_add_u32 s2, s18, s2
	s_addc_u32 s3, s19, 0
	global_load_dwordx4 v[156:159], v252, s[2:3]
	global_load_dwordx4 v[20:23], v252, s[2:3] offset:1024
	s_lshl_b32 s2, s86, 2
	v_writelane_b32 v147, s2, 1
	v_writelane_b32 v1, s87, 1
	s_and_b32 s88, s88, 0x3fff
	s_lshl_b32 s2, s88, 11
	s_add_u32 s2, s18, s2
	s_addc_u32 s3, s19, 0
	global_load_dwordx4 v[160:163], v252, s[2:3]
	global_load_dwordx4 v[24:27], v252, s[2:3] offset:1024
	s_lshl_b32 s2, s88, 2
	v_writelane_b32 v147, s2, 2
	v_writelane_b32 v1, s89, 2
	s_and_b32 s90, s90, 0x3fff
	s_lshl_b32 s2, s90, 11
	s_add_u32 s2, s18, s2
	s_addc_u32 s3, s19, 0
	global_load_dwordx4 v[164:167], v252, s[2:3]
	global_load_dwordx4 v[28:31], v252, s[2:3] offset:1024
	s_lshl_b32 s2, s90, 2
	v_writelane_b32 v147, s2, 3
	v_writelane_b32 v1, s91, 3
	global_load_dword v140, v147, s[44:45]
	global_load_dword v141, v147, s[46:47]
	v_dot4_i32_i8 v149, v72, v133, 0
	v_dot4_i32_i8 v150, v76, v133, 0
	v_dot4_i32_i8 v151, v80, v133, 0
	v_dot4_i32_i8 v148, v84, v133, 0
	v_dot4c_i32_i8_e32 v149, v73, v134
	v_dot4c_i32_i8_e32 v150, v77, v134
	v_dot4c_i32_i8_e32 v151, v81, v134
	v_dot4c_i32_i8_e32 v148, v85, v134
	v_dot4c_i32_i8_e32 v149, v74, v135
	v_dot4c_i32_i8_e32 v150, v78, v135
	v_dot4c_i32_i8_e32 v151, v82, v135
	v_dot4c_i32_i8_e32 v148, v86, v135
	v_dot4c_i32_i8_e32 v149, v75, v136
	v_dot4c_i32_i8_e32 v150, v79, v136
	v_dot4c_i32_i8_e32 v151, v83, v136
	v_dot4c_i32_i8_e32 v148, v87, v136
	s_add_i32 s3, s25, 3
	s_min_u32 s3, s3, 0x7f
	s_cmp_lt_u32 s3, 64
	s_cselect_b64 vcc, -1, 0
	s_nop 0
	v_cndmask_b32_e32 v249, v241, v240, vcc
	s_nop 1
	v_readlane_b32 s2, v249, s3
	s_and_b32 s3, s2, 31
	s_lshl_b32 s3, s3, 5
	s_bfe_u32 s94, s2, 0x20005
	s_lshl_b32 s2, s94, 11
	s_add_i32 s3, s3, s2
	s_load_dwordx8 s[84:91], s[36:37], s3
	v_cndmask_b32_e64 v143, v149, v150, s[0:1]
	v_cndmask_b32_e64 v144, v150, v149, s[0:1]
	v_cndmask_b32_e64 v145, v151, v148, s[0:1]
	v_cndmask_b32_e64 v146, v148, v151, s[0:1]
	s_nop 1
	v_add_u32_dpp v144, v143, v144 quad_perm:[1,0,3,2] row_mask:0xf bank_mask:0xf
	v_add_u32_dpp v146, v145, v146 quad_perm:[1,0,3,2] row_mask:0xf bank_mask:0xf
	s_nop 1
	v_cndmask_b32_e64 v143, v144, v146, s[6:7]
	v_cndmask_b32_e64 v145, v146, v144, s[6:7]
	s_nop 1
	v_add_u32_dpp v145, v143, v145 quad_perm:[2,3,0,1] row_mask:0xf bank_mask:0xf
	s_nop 1
	v_add_u32_dpp v145, v145, v145 row_ror:4 row_mask:0xf bank_mask:0xf
	s_nop 1
	v_add_u32_dpp v145, v145, v145 row_ror:8 row_mask:0xf bank_mask:0xf
	s_nop 1
	ds_bpermute_b32 v143, v126, v145
	s_waitcnt lgkmcnt(0)
	v_add_u32_e32 v145, v145, v143
	ds_bpermute_b32 v143, v127, v145
	s_waitcnt lgkmcnt(0)
	v_add_u32_e32 v145, v145, v143
	v_cvt_f32_i32_e32 v56, v145
	v_mul_f32_e32 v59, v88, v56
	v_mul_f32_e32 v59, v137, v59
	v_mul_f32_e32 v56, 0x3f3504f3, v59
	v_fma_f32 v143, |v56|, s66, v120
	v_fma_f32 v143, |v56|, v143, s67
	v_fma_f32 v143, |v56|, v143, s68
	v_fma_f32 v143, |v56|, v143, s69
	v_fma_f32 v143, |v56|, v143, s70
	v_fma_f32 v143, |v56|, v143, s71
	v_fma_f32 v143, |v56|, v143, |v56|
	v_mul_f32_e32 v144, 0xbfb8aa3b, v143
	v_fma_f32 v146, v143, s72, -v144
	v_rndne_f32_e32 v3, v144
	v_fmac_f32_e32 v146, 0xb2a5705f, v143
	v_sub_f32_e32 v144, v144, v3
	v_add_f32_e32 v144, v144, v146
	v_cvt_i32_f32_e32 v146, v3
	v_exp_f32_e32 v144, v144
	v_cmp_nlt_f32_e32 vcc, s73, v143
	v_ldexp_f32 v144, v144, v146
	s_nop 0
	v_cndmask_b32_e32 v144, 0, v144, vcc
	v_cmp_ngt_f32_e32 vcc, s74, v143
	s_nop 1
	v_cndmask_b32_e32 v143, v121, v144, vcc
	v_sub_f32_e32 v143, 1.0, v143
	v_mul_f32_e32 v168, v56, v56
	v_fmamk_f32 v169, v168, 0xba1345e1, v117
	v_fmaak_f32 v169, v168, v169, 0xbcdac9b8
	v_fmaak_f32 v169, v168, v169, 0x3de703be
	v_fmaak_f32 v169, v168, v169, 0xbec09330
	v_fmaak_f32 v168, v168, v169, 0x3e0375d0
	v_fma_f32 v168, |v56|, v168, |v56|
	v_cmp_nlt_f32_e64 vcc, |v56|, 1.0
	s_nop 1
	v_cndmask_b32_e32 v143, v168, v143, vcc
	v_bfi_b32 v146, s75, v143, v56
	v_mul_f32_e32 v145, 0.5, v59
	v_add_f32_e32 v146, 1.0, v146
	v_mul_f32_e32 v145, v145, v146
	v_mul_f32_e32 v144, v2, v145
	v_mul_f32_e32 v143, v89, v144
	s_nop 1
	v_readlane_b32 s40, v143, 0
	v_readlane_b32 s38, v143, 1
	v_readlane_b32 s42, v143, 2
	v_readlane_b32 s2, v143, 3
	s_nop 1
	v_add_f32_e32 v142, s40, v142
	v_add_f32_e32 v142, s38, v142
	v_add_f32_e32 v142, s42, v142
	v_add_f32_e32 v142, s2, v142
	v_cvt_f32_ubyte1_e32 v169, v64
	v_cvt_f32_ubyte0_e32 v168, v64
	v_pk_fma_f32 v[104:105], s[40:41], v[168:169], v[104:105] op_sel_hi:[0,1,1]
	v_cvt_f32_ubyte1_e32 v171, v68
	v_cvt_f32_ubyte0_e32 v170, v68
	v_pk_fma_f32 v[104:105], s[38:39], v[170:171], v[104:105] op_sel_hi:[0,1,1]
	v_cvt_f32_ubyte1_e32 v169, v4
	v_cvt_f32_ubyte0_e32 v168, v4
	v_pk_fma_f32 v[104:105], s[42:43], v[168:169], v[104:105] op_sel_hi:[0,1,1]
	v_cvt_f32_ubyte1_e32 v171, v128
	v_cvt_f32_ubyte0_e32 v170, v128
	v_pk_fma_f32 v[104:105], s[2:3], v[170:171], v[104:105] op_sel_hi:[0,1,1]
	v_cvt_f32_ubyte3_e32 v169, v64
	v_cvt_f32_ubyte2_e32 v168, v64
	v_pk_fma_f32 v[102:103], s[40:41], v[168:169], v[102:103] op_sel_hi:[0,1,1]
	v_cvt_f32_ubyte3_e32 v171, v68
	v_cvt_f32_ubyte2_e32 v170, v68
	v_pk_fma_f32 v[102:103], s[38:39], v[170:171], v[102:103] op_sel_hi:[0,1,1]
	v_cvt_f32_ubyte3_e32 v169, v4
	v_cvt_f32_ubyte2_e32 v168, v4
	v_pk_fma_f32 v[102:103], s[42:43], v[168:169], v[102:103] op_sel_hi:[0,1,1]
	v_cvt_f32_ubyte3_e32 v171, v128
	v_cvt_f32_ubyte2_e32 v170, v128
	v_pk_fma_f32 v[102:103], s[2:3], v[170:171], v[102:103] op_sel_hi:[0,1,1]
	v_cvt_f32_ubyte1_e32 v169, v65
	v_cvt_f32_ubyte0_e32 v168, v65
	v_pk_fma_f32 v[98:99], s[40:41], v[168:169], v[98:99] op_sel_hi:[0,1,1]
	v_cvt_f32_ubyte1_e32 v171, v69
	v_cvt_f32_ubyte0_e32 v170, v69
	v_pk_fma_f32 v[98:99], s[38:39], v[170:171], v[98:99] op_sel_hi:[0,1,1]
	v_cvt_f32_ubyte1_e32 v169, v5
	v_cvt_f32_ubyte0_e32 v168, v5
	v_pk_fma_f32 v[98:99], s[42:43], v[168:169], v[98:99] op_sel_hi:[0,1,1]
	v_cvt_f32_ubyte1_e32 v171, v129
	v_cvt_f32_ubyte0_e32 v170, v129
	v_pk_fma_f32 v[98:99], s[2:3], v[170:171], v[98:99] op_sel_hi:[0,1,1]
	v_cvt_f32_ubyte3_e32 v169, v65
	v_cvt_f32_ubyte2_e32 v168, v65
	v_pk_fma_f32 v[100:101], s[40:41], v[168:169], v[100:101] op_sel_hi:[0,1,1]
	v_cvt_f32_ubyte3_e32 v171, v69
	v_cvt_f32_ubyte2_e32 v170, v69
	v_pk_fma_f32 v[100:101], s[38:39], v[170:171], v[100:101] op_sel_hi:[0,1,1]
	v_cvt_f32_ubyte3_e32 v169, v5
	v_cvt_f32_ubyte2_e32 v168, v5
	v_pk_fma_f32 v[100:101], s[42:43], v[168:169], v[100:101] op_sel_hi:[0,1,1]
	v_cvt_f32_ubyte3_e32 v171, v129
	v_cvt_f32_ubyte2_e32 v170, v129
	v_pk_fma_f32 v[100:101], s[2:3], v[170:171], v[100:101] op_sel_hi:[0,1,1]
	v_cvt_f32_ubyte1_e32 v169, v66
	v_cvt_f32_ubyte0_e32 v168, v66
	v_pk_fma_f32 v[94:95], s[40:41], v[168:169], v[94:95] op_sel_hi:[0,1,1]
	v_cvt_f32_ubyte1_e32 v171, v70
	v_cvt_f32_ubyte0_e32 v170, v70
	v_pk_fma_f32 v[94:95], s[38:39], v[170:171], v[94:95] op_sel_hi:[0,1,1]
	v_cvt_f32_ubyte1_e32 v169, v6
	v_cvt_f32_ubyte0_e32 v168, v6
	v_pk_fma_f32 v[94:95], s[42:43], v[168:169], v[94:95] op_sel_hi:[0,1,1]
	v_cvt_f32_ubyte1_e32 v171, v130
	v_cvt_f32_ubyte0_e32 v170, v130
	v_pk_fma_f32 v[94:95], s[2:3], v[170:171], v[94:95] op_sel_hi:[0,1,1]
	v_cvt_f32_ubyte3_e32 v169, v66
	v_cvt_f32_ubyte2_e32 v168, v66
	v_pk_fma_f32 v[96:97], s[40:41], v[168:169], v[96:97] op_sel_hi:[0,1,1]
	v_cvt_f32_ubyte3_e32 v171, v70
	v_cvt_f32_ubyte2_e32 v170, v70
	v_pk_fma_f32 v[96:97], s[38:39], v[170:171], v[96:97] op_sel_hi:[0,1,1]
	v_cvt_f32_ubyte3_e32 v169, v6
	v_cvt_f32_ubyte2_e32 v168, v6
	v_pk_fma_f32 v[96:97], s[42:43], v[168:169], v[96:97] op_sel_hi:[0,1,1]
	v_cvt_f32_ubyte3_e32 v171, v130
	v_cvt_f32_ubyte2_e32 v170, v130
	v_pk_fma_f32 v[96:97], s[2:3], v[170:171], v[96:97] op_sel_hi:[0,1,1]
	v_cvt_f32_ubyte1_e32 v169, v67
	v_cvt_f32_ubyte0_e32 v168, v67
	v_pk_fma_f32 v[90:91], s[40:41], v[168:169], v[90:91] op_sel_hi:[0,1,1]
	v_cvt_f32_ubyte1_e32 v171, v71
	v_cvt_f32_ubyte0_e32 v170, v71
	v_pk_fma_f32 v[90:91], s[38:39], v[170:171], v[90:91] op_sel_hi:[0,1,1]
	v_cvt_f32_ubyte1_e32 v169, v7
	v_cvt_f32_ubyte0_e32 v168, v7
	v_pk_fma_f32 v[90:91], s[42:43], v[168:169], v[90:91] op_sel_hi:[0,1,1]
	v_cvt_f32_ubyte1_e32 v171, v131
	v_cvt_f32_ubyte0_e32 v170, v131
	v_pk_fma_f32 v[90:91], s[2:3], v[170:171], v[90:91] op_sel_hi:[0,1,1]
	v_cvt_f32_ubyte3_e32 v169, v67
	v_cvt_f32_ubyte2_e32 v168, v67
	v_pk_fma_f32 v[92:93], s[40:41], v[168:169], v[92:93] op_sel_hi:[0,1,1]
	v_cvt_f32_ubyte3_e32 v171, v71
	v_cvt_f32_ubyte2_e32 v170, v71
	v_pk_fma_f32 v[92:93], s[38:39], v[170:171], v[92:93] op_sel_hi:[0,1,1]
	v_cvt_f32_ubyte3_e32 v169, v7
	v_cvt_f32_ubyte2_e32 v168, v7
	v_pk_fma_f32 v[92:93], s[42:43], v[168:169], v[92:93] op_sel_hi:[0,1,1]
	v_cvt_f32_ubyte3_e32 v171, v131
	v_cvt_f32_ubyte2_e32 v170, v131
	v_pk_fma_f32 v[92:93], s[2:3], v[170:171], v[92:93] op_sel_hi:[0,1,1]
	s_waitcnt vmcnt(10) lgkmcnt(0)
	s_cmp_eq_u32 s80, s33
	s_cbranch_scc1 .Lxp_noswc
	s_lshl_b32 s2, s33, 12
	v_add_u32_e32 v249, s2, v248
	ds_write_b128 v249, v[90:93]
	ds_write_b128 v249, v[94:97] offset:1024
	ds_write_b128 v249, v[98:101] offset:2048
	ds_write_b128 v249, v[102:105] offset:3072
	v_cmp_eq_u32_e32 vcc, s33, v60
	s_nop 1
	v_cndmask_b32_e32 v243, v243, v142, vcc
	s_lshl_b32 s2, s80, 12
	v_add_u32_e32 v249, s2, v248
	ds_read_b128 v[90:93], v249
	ds_read_b128 v[94:97], v249 offset:1024
	ds_read_b128 v[98:101], v249 offset:2048
	ds_read_b128 v[102:105], v249 offset:3072
	s_nop 0
	v_readlane_b32 s2, v243, s80
	v_readlane_b32 s3, v244, s80
	s_nop 1
	v_mov_b32_e32 v142, s2
	v_mov_b32_e32 v137, s3
	s_cmp_eq_u32 s80, 0
	s_cbranch_scc1 .Lxp_lxqc0
	s_cmp_eq_u32 s80, 1
	s_cbranch_scc1 .Lxp_lxqc1
	s_cmp_eq_u32 s80, 2
	s_cbranch_scc1 .Lxp_lxqc2
	v_mov_b32_e32 v133, v236
	v_mov_b32_e32 v134, v237
	v_mov_b32_e32 v135, v238
	v_mov_b32_e32 v136, v239
	s_branch .Lxp_lxqcd
